# phase 5 tile queue: next tile index claimed one tile ahead (atomic round trip overlaps the conversion), LDS broadcast via ds ops; plus prep quarter shift
# baseline (speedup 1.0000x reference)
.Lser_exit:
	s_nop 0
	s_nop 0
	s_nop 0
	s_nop 0
	s_nop 0
	v_lshlrev_b32_e32 v157, 2, v0
.LBB0_506:
	s_add_u32 s10, s70, 0x15c88000
	s_addc_u32 s11, s71, 0
	s_add_u32 s12, s70, 0x6e00000
	s_addc_u32 s13, s71, 0
	s_add_u32 s14, s70, 0x6a00000
	s_addc_u32 s15, s71, 0
	s_add_u32 s16, s70, 0x6600000
	s_addc_u32 s17, s71, 0
	v_lshlrev_b32_e32 v2, 3, v0
	s_add_u32 s18, s70, 0x3a00000
	v_and_b32_e32 v2, 56, v2
	s_addc_u32 s19, s71, 0
	v_lshlrev_b32_e32 v1, 2, v157
	s_waitcnt vmcnt(8)
	v_lshrrev_b32_e32 v58, 3, v0
	v_mul_u32_u24_e32 v5, 0x41, v2
	s_waitcnt lgkmcnt(0)
	s_cmp_lg_u64 s[50:51], 0
	v_lshrrev_b32_e32 v34, 4, v0
	v_and_b32_e32 v36, 0xf0, v1
	v_lshlrev_b32_e32 v4, 2, v58
	v_lshlrev_b32_e32 v5, 2, v5
	s_cselect_b64 s[22:23], -1, 0
	s_add_u32 s24, s70, 0x1600000
	v_mov_b32_e32 v37, 0
	v_add_u32_e32 v1, 0, v36
	v_mul_u32_u24_e32 v3, 0x104, v34
	v_add3_u32 v60, 0, v5, v4
	s_addc_u32 s25, s71, 0
	s_mov_b64 s[8:9], src_shared_base
	v_add3_u32 v59, 0, v4, v5
	v_add_u32_e32 v61, 0x4100, v60
	s_waitcnt vmcnt(7)
	v_add_u32_e32 v62, 0x8200, v60
	v_lshl_add_u64 v[40:41], s[46:47], 0, v[36:37]
	s_mov_b64 s[6:7], 0x800000
	v_or_b32_e32 v4, 32, v34
	s_cmp_lg_u64 s[38:39], 0
	v_add_u32_e32 v65, v1, v3
	v_lshl_add_u64 v[38:39], s[48:49], 0, v[36:37]
	v_add_u32_e32 v63, 0xc300, v60
	v_lshl_add_u64 v[42:43], v[40:41], 0, s[6:7]
	v_lshl_add_u64 v[44:45], s[58:59], 0, v[36:37]
	v_lshl_add_u64 v[46:47], s[52:53], 0, v[36:37]
	s_mov_b64 s[20:21], 0
	v_mul_u32_u24_e32 v64, 0x104, v4
	v_lshl_add_u64 v[48:49], s[40:41], 0, v[36:37]
	s_cselect_b64 s[26:27], -1, 0
	v_mov_b32_e32 v35, v37
	s_add_i32 s3, 0, 0x18000
	s_movk_i32 s8, 0x780
	s_movk_i32 s64, 0x580
	s_movk_i32 s65, 0x47f
	s_movk_i32 s66, 0x9ff
	s_movk_i32 s67, 0xcbf
	s_movk_i32 s74, 0xd3f
	s_movk_i32 s75, 0xdbf
	s_waitcnt vmcnt(6)
	v_add_u32_e32 v66, 0x2080, v65
	v_add_u32_e32 v67, 0x2088, v65
	v_add_u32_e32 v68, 0x4100, v65
	v_add_u32_e32 v69, 0x4108, v65
	s_waitcnt vmcnt(5)
	v_add_u32_e32 v70, 0x6180, v65
	v_add_u32_e32 v71, 0x6188, v65
	v_add_u32_e32 v72, 0x8200, v65
	v_add_u32_e32 v73, 0x8208, v65
	s_waitcnt vmcnt(4)
	v_add_u32_e32 v74, 0xa280, v65
	v_add_u32_e32 v75, 0xa288, v65
	v_add_u32_e32 v76, 0xc300, v65
	v_add_u32_e32 v77, 0xc308, v65
	s_waitcnt vmcnt(3)
	v_add_u32_e32 v78, 0xe380, v65
	v_add_u32_e32 v79, 0xe388, v65
	s_mov_b32 s76, 0x160000
	s_mov_b32 s77, 0x2c0000
	s_mov_b32 s78, 0x420000
	s_mov_b32 s79, 0x580000
	s_mov_b32 s80, 0x38e38e39
	s_movk_i32 s81, 0x90
	s_mov_b32 s82, 0x8f00
	v_mov_b32_e32 v80, 0x740
	v_mov_b32_e32 v81, 0x480
	s_waitcnt vmcnt(2)
	v_add_u32_e32 v82, 0x200, v60
	v_add_u32_e32 v83, 0x400, v60
	v_lshlrev_b32_e32 v50, 1, v2
	v_add_u32_e32 v84, 0x200, v61
	v_add_u32_e32 v85, 0x400, v61
	s_waitcnt vmcnt(1)
	v_add_u32_e32 v86, 0x200, v62
	v_add_u32_e32 v87, 0x400, v62
	v_mov_b32_e32 v251, 1
	s_and_saveexec_b64 s[6:7], s[4:5]
	global_atomic_add v250, v37, v251, s[10:11] sc0
	s_mov_b64 exec, s[6:7]
	s_branch .LBB0_510

.LBB0_510:
	s_barrier
	s_and_saveexec_b64 s[6:7], s[4:5]
	s_cbranch_execz .LBB0_514
	s_waitcnt vmcnt(0)
	v_mov_b32_e32 v2, s3
	ds_write_b32 v2, v250
	global_atomic_add v250, v37, v251, s[10:11] sc0
.LBB0_514:
	s_or_b64 exec, exec, s[6:7]
	v_mov_b32_e32 v2, s3
	s_waitcnt lgkmcnt(0)
	s_barrier
	ds_read_b32 v2, v2
	s_mov_b64 s[6:7], -1
	s_waitcnt lgkmcnt(0)
	v_cmp_gt_i32_e32 vcc, s8, v2
	s_and_saveexec_b64 s[28:29], vcc
	s_cbranch_execz .LBB0_509
	v_cmp_gt_i32_e32 vcc, s64, v2
	s_nop 1
	v_cndmask_b32_e32 v3, v80, v81, vcc
	v_add_u32_e32 v3, v3, v2
	v_cmp_lt_i32_e32 vcc, s65, v3
	s_and_saveexec_b64 s[6:7], vcc
	s_xor_b64 s[30:31], exec, s[6:7]
	s_cbranch_execz .LBB0_539
	v_cmp_lt_u32_e32 vcc, s66, v3
	s_and_saveexec_b64 s[6:7], vcc
	s_xor_b64 s[6:7], exec, s[6:7]
	s_cbranch_execz .LBB0_530
	v_cmp_lt_u32_e32 vcc, s67, v3
	s_and_saveexec_b64 s[42:43], vcc
	s_xor_b64 s[44:45], exec, s[42:43]
	s_cbranch_execz .LBB0_527
	v_cmp_lt_u32_e32 vcc, s74, v3
	s_and_saveexec_b64 s[42:43], vcc
	s_xor_b64 s[46:47], exec, s[42:43]
	s_cbranch_execz .LBB0_524
	v_lshlrev_b32_e32 v2, 6, v3
	v_and_b32_e32 v2, 0x7c0, v2
	v_cmp_lt_u32_e32 vcc, s75, v3
	v_lshlrev_b32_e32 v3, 3, v3
	v_lshlrev_b32_e32 v36, 2, v2
	s_and_saveexec_b64 s[42:43], vcc
	s_xor_b64 s[48:49], exec, s[42:43]
	s_cbranch_execz .LBB0_521
	v_and_b32_e32 v3, 0x7fffff00, v3
	v_add_u32_e32 v32, 0xffff9200, v3
	v_or_b32_e32 v24, v32, v34
	v_lshl_add_u64 v[52:53], v[38:39], 0, v[36:37]
	v_or_b32_e32 v36, 32, v24
	v_lshlrev_b64 v[6:7], 13, v[36:37]
	v_or_b32_e32 v36, 64, v24
	v_mov_b32_e32 v25, v37
	v_lshl_add_u64 v[8:9], v[52:53], 0, v[6:7]
	v_lshlrev_b64 v[6:7], 13, v[36:37]
	v_or_b32_e32 v36, 0x60, v24
	v_lshlrev_b64 v[4:5], 13, v[24:25]
	v_lshl_add_u64 v[12:13], v[52:53], 0, v[6:7]
	v_lshlrev_b64 v[6:7], 13, v[36:37]
	v_or_b32_e32 v36, 0x80, v24
	v_lshl_add_u64 v[4:5], v[52:53], 0, v[4:5]
	v_lshl_add_u64 v[16:17], v[52:53], 0, v[6:7]
	v_lshlrev_b64 v[6:7], 13, v[36:37]
	v_lshl_add_u64 v[20:21], v[52:53], 0, v[6:7]
	v_or_b32_e32 v36, 0xa0, v24
	global_load_dwordx4 v[4:7], v[4:5], off
	v_lshlrev_b64 v[10:11], 13, v[36:37]
	v_lshl_add_u64 v[26:27], v[52:53], 0, v[10:11]
	global_load_dwordx4 v[8:11], v[8:9], off
	v_or_b32_e32 v36, 0xc0, v24
	global_load_dwordx4 v[12:15], v[12:13], off
	v_lshlrev_b64 v[22:23], 13, v[36:37]
	global_load_dwordx4 v[16:19], v[16:17], off
	v_lshl_add_u64 v[28:29], v[52:53], 0, v[22:23]
	global_load_dwordx4 v[20:23], v[20:21], off
	v_or_b32_e32 v36, 0xe0, v24
	global_load_dwordx4 v[24:27], v[26:27], off
	v_lshlrev_b64 v[54:55], 13, v[36:37]
	global_load_dwordx4 v[28:31], v[28:29], off
	v_lshl_add_u64 v[52:53], v[52:53], 0, v[54:55]
	global_load_dwordx4 v[52:55], v[52:53], off
	v_add_lshl_u32 v36, v2, v58, 12
	v_mov_b32_e32 v33, v37
	v_lshl_add_u64 v[2:3], s[12:13], 0, v[36:37]
	v_mov_b32_e32 v51, v37
	v_lshl_add_u64 v[2:3], v[32:33], 1, v[2:3]
	v_add_u32_e32 v56, 0x200, v63
	v_add_u32_e32 v57, 0x400, v63
	v_lshl_add_u64 v[32:33], v[2:3], 0, v[50:51]
	s_waitcnt vmcnt(7)
	ds_write2_b32 v65, v4, v5 offset1:1
	ds_write2_b32 v65, v6, v7 offset0:2 offset1:3
	s_waitcnt vmcnt(6)
	ds_write2_b32 v66, v8, v9 offset1:1
	ds_write2_b32 v67, v10, v11 offset1:1
	s_waitcnt vmcnt(5)
	ds_write2_b32 v68, v12, v13 offset1:1
	ds_write2_b32 v69, v14, v15 offset1:1
	s_waitcnt vmcnt(4)
	ds_write2_b32 v70, v16, v17 offset1:1
	ds_write2_b32 v71, v18, v19 offset1:1
	s_waitcnt vmcnt(3)
	ds_write2_b32 v72, v20, v21 offset1:1
	ds_write2_b32 v73, v22, v23 offset1:1
	s_waitcnt vmcnt(2)
	ds_write2_b32 v74, v24, v25 offset1:1
	ds_write2_b32 v75, v26, v27 offset1:1
	s_waitcnt vmcnt(1)
	ds_write2_b32 v76, v28, v29 offset1:1
	ds_write2_b32 v77, v30, v31 offset1:1
	s_waitcnt vmcnt(0)
	ds_write2_b32 v78, v52, v53 offset1:1
	ds_write2_b32 v79, v54, v55 offset1:1
	s_waitcnt lgkmcnt(0)
	s_barrier
	ds_read2_b32 v[2:3], v60 offset0:65 offset1:130
	ds_read2_b32 v[4:5], v82 offset0:67 offset1:132
	ds_read2_b32 v[6:7], v83 offset0:69 offset1:134
	ds_read2_b32 v[8:9], v61 offset0:65 offset1:130
	ds_read2_b32 v[10:11], v84 offset0:67 offset1:132
	ds_read2_b32 v[12:13], v85 offset0:69 offset1:134
	ds_read2_b32 v[14:15], v62 offset0:65 offset1:130
	ds_read2_b32 v[16:17], v86 offset0:67 offset1:132
	ds_read2_b32 v[18:19], v87 offset0:69 offset1:134
	ds_read2_b32 v[20:21], v63 offset0:65 offset1:130
	ds_read2_b32 v[22:23], v56 offset0:67 offset1:132
	ds_read2_b32 v[24:25], v57 offset0:69 offset1:134
	ds_read_b32 v26, v59
	ds_read_b32 v27, v60 offset:1820
	ds_read_b32 v28, v60 offset:16640
	ds_read_b32 v29, v61 offset:1820
	ds_read_b32 v30, v61 offset:16640
	ds_read_b32 v31, v62 offset:1820
	ds_read_b32 v36, v62 offset:16640
	ds_read_b32 v51, v63 offset:1820
	s_waitcnt lgkmcnt(7)
	v_cvt_pk_bf16_f32 v2, v26, v2
	v_cvt_pk_bf16_f32 v3, v3, v4
	v_cvt_pk_bf16_f32 v4, v5, v6
	s_waitcnt lgkmcnt(6)
	v_cvt_pk_bf16_f32 v5, v7, v27
	s_waitcnt lgkmcnt(5)
	v_cvt_pk_bf16_f32 v6, v28, v8
	v_cvt_pk_bf16_f32 v7, v9, v10
	v_cvt_pk_bf16_f32 v8, v11, v12
	s_waitcnt lgkmcnt(3)
	v_cvt_pk_bf16_f32 v10, v30, v14
	v_cvt_pk_bf16_f32 v11, v15, v16
	v_cvt_pk_bf16_f32 v12, v17, v18
	s_waitcnt lgkmcnt(1)
	v_cvt_pk_bf16_f32 v14, v36, v20
	v_cvt_pk_bf16_f32 v15, v21, v22
	v_cvt_pk_bf16_f32 v16, v23, v24
	s_waitcnt lgkmcnt(0)
	v_cvt_pk_bf16_f32 v17, v25, v51
	v_cvt_pk_bf16_f32 v9, v13, v29
	v_cvt_pk_bf16_f32 v13, v19, v31
	global_store_dwordx4 v[32:33], v[2:5], off
	global_store_dwordx4 v[32:33], v[6:9], off offset:128
	global_store_dwordx4 v[32:33], v[10:13], off offset:256
	global_store_dwordx4 v[32:33], v[14:17], off offset:384
	s_waitcnt lgkmcnt(0)
	s_barrier
